# P7 epilogue: three of the four column-step quads loaded before the unit's K-loop into phase-dead registers, fourth issued at the head and waited at first use (no vmcnt(0) drain at the epilogue head)
# baseline (speedup 1.0000x reference)
;     __device__ __forceinline__ void operator()(const i32x4 (&acc)[2][2][4][2], const Unit& u, int wr, int wc, int fr, int fq) const {
;     ...
;         for (int bj = 0; bj < 2; ++bj) { const u32x4 cb0 = *(const u32x4*)(cmax + col0 + bj * HALF), cb1 = *(const u32x4*)(cmax + col0 + bj * HALF + 4);
; template <class Epi, class Sched, bool ALIGN_EPI = false, bool SP2 = false, bool TILED_A = false, bool TILED_B = false, bool I8 = false>
; __device__ __forceinline__ void gemm_phase(PG8_LAS unsigned char* lds, const Gemm g, const Sched& S, const Epi& E) {
;     ...
; #pragma unroll
;         for (int a = 0; a < 2; ++a)
; #pragma unroll
;             for (int b = 0; b < 2; ++b)
; #pragma unroll
;                 for (int m = 0; m < 4; ++m)
; #pragma unroll
;                     for (int n = 0; n < 2; ++n) acc[a][b][m][n] = MT<I8>::zero();
;         cur = nxt; cA = nA; cB = nB; ++ui;
.LBB0_717:
	s_ashr_i32 s55, s54, 31
	s_lshl_b64 s[12:13], s[54:55], 20
	s_add_u32 s56, s20, s12
	s_addc_u32 s57, s25, s13
	s_and_b64 s[12:13], s[44:45], exec
	s_cselect_b32 s3, s57, s11
	s_cselect_b32 s9, s56, s10
	s_ashr_i32 s53, s52, 31
	s_lshl_b64 s[12:13], s[52:53], 20
	s_add_u32 s58, s26, s12
	s_addc_u32 s59, s27, s13
	s_and_b64 s[12:13], s[44:45], exec
	s_cselect_b32 s22, s59, s7
	s_cselect_b32 s23, s58, s6
	s_add_u32 s24, s6, 0x10000
	s_addc_u32 s48, s7, 0
	s_add_u32 s6, s10, 0x80080
	v_mov_b32_e32 v2, 0
	s_addc_u32 s7, s11, 0
	s_mov_b32 s53, -2
	s_waitcnt lgkmcnt(0)
	v_mov_b32_e32 v3, v2
	v_mov_b32_e32 v4, v2
	v_mov_b32_e32 v5, v2
	v_mov_b32_e32 v6, v2
	v_mov_b32_e32 v7, v2
	v_mov_b32_e32 v8, v2
	v_mov_b32_e32 v9, v2
	v_mov_b32_e32 v18, v2
	v_mov_b32_e32 v19, v2
	v_mov_b32_e32 v20, v2
	v_mov_b32_e32 v21, v2
	v_mov_b32_e32 v22, v2
	v_mov_b32_e32 v23, v2
	v_mov_b32_e32 v24, v2
	v_mov_b32_e32 v25, v2
	v_mov_b32_e32 v34, v2
	v_mov_b32_e32 v35, v2
	v_mov_b32_e32 v36, v2
	v_mov_b32_e32 v37, v2
	v_mov_b32_e32 v38, v2
	v_mov_b32_e32 v39, v2
	v_mov_b32_e32 v40, v2
	v_mov_b32_e32 v41, v2
	v_mov_b32_e32 v50, v2
	v_mov_b32_e32 v51, v2
	v_mov_b32_e32 v52, v2
	v_mov_b32_e32 v53, v2
	v_mov_b32_e32 v54, v2
	v_mov_b32_e32 v55, v2
	v_mov_b32_e32 v56, v2
	v_mov_b32_e32 v57, v2
	v_mov_b32_e32 v10, v2
	v_mov_b32_e32 v11, v2
	v_mov_b32_e32 v12, v2
	v_mov_b32_e32 v13, v2
	v_mov_b32_e32 v14, v2
	v_mov_b32_e32 v15, v2
	v_mov_b32_e32 v16, v2
	v_mov_b32_e32 v17, v2
	v_mov_b32_e32 v26, v2
	v_mov_b32_e32 v27, v2
	v_mov_b32_e32 v28, v2
	v_mov_b32_e32 v29, v2
	v_mov_b32_e32 v30, v2
	v_mov_b32_e32 v31, v2
	v_mov_b32_e32 v32, v2
	v_mov_b32_e32 v33, v2
	v_mov_b32_e32 v42, v2
	v_mov_b32_e32 v43, v2
	v_mov_b32_e32 v44, v2
	v_mov_b32_e32 v45, v2
	v_mov_b32_e32 v46, v2
	v_mov_b32_e32 v47, v2
	v_mov_b32_e32 v48, v2
	v_mov_b32_e32 v49, v2
	v_mov_b32_e32 v58, v2
	v_mov_b32_e32 v59, v2
	v_mov_b32_e32 v60, v2
	v_mov_b32_e32 v61, v2
	v_mov_b32_e32 v62, v2
	v_mov_b32_e32 v63, v2
	v_mov_b32_e32 v64, v2
	v_mov_b32_e32 v65, v2
	v_mov_b32_e32 v66, v2
	v_mov_b32_e32 v67, v2
	v_mov_b32_e32 v68, v2
	v_mov_b32_e32 v69, v2
	v_mov_b32_e32 v70, v2
	v_mov_b32_e32 v71, v2
	v_mov_b32_e32 v72, v2
	v_mov_b32_e32 v73, v2
	v_mov_b32_e32 v82, v2
	v_mov_b32_e32 v83, v2
	v_mov_b32_e32 v84, v2
	v_mov_b32_e32 v85, v2
	v_mov_b32_e32 v86, v2
	v_mov_b32_e32 v87, v2
	v_mov_b32_e32 v88, v2
	v_mov_b32_e32 v89, v2
	v_mov_b32_e32 v98, v2
	v_mov_b32_e32 v99, v2
	v_mov_b32_e32 v100, v2
	v_mov_b32_e32 v101, v2
	v_mov_b32_e32 v102, v2
	v_mov_b32_e32 v103, v2
	v_mov_b32_e32 v104, v2
	v_mov_b32_e32 v105, v2
	v_mov_b32_e32 v116, v2
	v_mov_b32_e32 v117, v2
	v_mov_b32_e32 v118, v2
	v_mov_b32_e32 v119, v2
	v_mov_b32_e32 v120, v2
	v_mov_b32_e32 v121, v2
	v_mov_b32_e32 v122, v2
	v_mov_b32_e32 v123, v2
	v_mov_b32_e32 v74, v2
	v_mov_b32_e32 v75, v2
	v_mov_b32_e32 v76, v2
	v_mov_b32_e32 v77, v2
	v_mov_b32_e32 v78, v2
	v_mov_b32_e32 v79, v2
	v_mov_b32_e32 v80, v2
	v_mov_b32_e32 v81, v2
	v_mov_b32_e32 v90, v2
	v_mov_b32_e32 v91, v2
	v_mov_b32_e32 v92, v2
	v_mov_b32_e32 v93, v2
	v_mov_b32_e32 v94, v2
	v_mov_b32_e32 v95, v2
	v_mov_b32_e32 v96, v2
	v_mov_b32_e32 v97, v2
	v_mov_b32_e32 v106, v2
	v_mov_b32_e32 v107, v2
	v_mov_b32_e32 v108, v2
	v_mov_b32_e32 v109, v2
	v_mov_b32_e32 v110, v2
	v_mov_b32_e32 v111, v2
	v_mov_b32_e32 v112, v2
	v_mov_b32_e32 v113, v2
	v_mov_b32_e32 v124, v2
	v_mov_b32_e32 v125, v2
	v_mov_b32_e32 v126, v2
	v_mov_b32_e32 v127, v2
	v_mov_b32_e32 v128, v2
	v_mov_b32_e32 v129, v2
	v_mov_b32_e32 v130, v2
	v_mov_b32_e32 v131, v2
	v_lshl_or_b32 v202, s2, 8, v153
	v_lshlrev_b32_e32 v202, 2, v202
	global_load_dwordx4 v[238:241], v202, s[46:47] offset:16
	global_load_dwordx4 v[242:245], v202, s[46:47]
	global_load_dwordx4 v[246:249], v202, s[46:47] offset:528

; __device__ __forceinline__ unsigned cvt_pk_bf16(float lo, float hi) { unsigned r; asm volatile("v_cvt_pk_bf16_f32 %0, %1, %2" : "=v"(r) : "v"(lo), "v"(hi)); return r; }
;     __device__ __forceinline__ void operator()(const i32x4 (&acc)[2][2][4][2], const Unit& u, int wr, int wc, int fr, int fq) const {
;     ...
;         const int col0 = u.pn * BM + wc * 32 + 8 * fq, lane = fr + 16 * fq;
;         float cs[2][8];
; #pragma unroll
;         for (int bj = 0; bj < 2; ++bj) { const u32x4 cb0 = *(const u32x4*)(cmax + col0 + bj * HALF), cb1 = *(const u32x4*)(cmax + col0 + bj * HALF + 4);
; #pragma unroll
;             for (int e = 0; e < 4; ++e) { cs[bj][e] = __uint_as_float(cb0[e]) * (1.0f / 127.0f); cs[bj][4 + e] = __uint_as_float(cb1[e]) * (1.0f / 127.0f); } }
; #pragma unroll
;         for (int ai = 0; ai < 2; ++ai)
; #pragma unroll
;             for (int m = 0; m < 4; ++m) { const int rl = wr * 64 + fr + ai * HALF + m * 16;
;                 bf16_t* rowp = O + ((((size_t)u.pm * (ldc >> 6) + (u.pn * 4 + (wc >> 1))) * 256 + rl) * 64 + (wc & 1) * 32 + 8 * fq);
;                 float tm = 0.f;
; #pragma unroll
;                 for (int bj = 0; bj < 2; ++bj) { float v[8];
; #pragma unroll
;                     for (int e = 0; e < 4; ++e) { const float a = fmaxf((float)acc[ai][bj][m][0][e] * cs[bj][e], 0.f), b = fmaxf((float)acc[ai][bj][m][1][e] * cs[bj][4 + e], 0.f);
;                         tm = fmaxf(tm, fmaxf(a, b)); v[e] = a * a; v[4 + e] = b * b; }
;                     u32x4 w; w.x = cvt_pk_bf16(v[0], v[1]); w.y = cvt_pk_bf16(v[2], v[3]); w.z = cvt_pk_bf16(v[4], v[5]); w.w = cvt_pk_bf16(v[6], v[7]);
;                     *(u32x4*)(rowp + bj * 2 * 256 * 64) = w; }
;                 if (rmax) {
;                     tm = fmaxf(tm, __int_as_float(__builtin_amdgcn_ds_bpermute((lane ^ 16) << 2, __float_as_int(tm))));
;                     tm = fmaxf(tm, __int_as_float(__builtin_amdgcn_ds_bpermute((lane ^ 32) << 2, __float_as_int(tm))));
;                     if (fq == 0) (void)__hip_atomic_fetch_max(rmax + u.pm * BM + rl, __float_as_uint(tm), __ATOMIC_RELAXED, __HIP_MEMORY_SCOPE_AGENT); } }
.LBB0_721:
	v_lshl_or_b32 v146, s2, 8, v153
	v_ashrrev_i32_e32 v147, 31, v146
	v_mov_b32_e32 v145, v1
	v_lshl_add_u64 v[150:151], v[146:147], 2, s[46:47]
	global_load_dwordx4 v[174:177], v[150:151], off offset:512
	s_lshl_b32 s2, s2, 2
	s_or_b32 s2, s2, s70
	s_ashr_i32 s9, s8, 31
	s_ashr_i32 s3, s2, 31
	s_lshl_b32 s6, s8, 8
	s_ashr_i32 s7, s6, 31
	s_lshl_b64 s[8:9], s[8:9], 23
	s_lshl_b64 s[2:3], s[2:3], 15
	v_cvt_f32_i32_e32 v129, v129
	v_cvt_f32_i32_e32 v125, v125
	v_cvt_f32_i32_e32 v130, v130
	s_add_u32 s8, s37, s8
	v_cvt_f32_i32_e32 v128, v128
	v_cvt_f32_i32_e32 v124, v124
	v_cvt_f32_i32_e32 v126, v126
	v_cvt_f32_i32_e32 v131, v131
	s_addc_u32 s9, s60, s9
	v_cvt_f32_i32_e32 v127, v127
	s_add_u32 s2, s8, s2
	v_cvt_f32_i32_e32 v118, v118
	s_addc_u32 s3, s9, s3
	s_lshl_b32 s48, s71, 1
	v_cvt_f32_i32_e32 v120, v120
	v_cvt_f32_i32_e32 v116, v116
	v_cvt_f32_i32_e32 v121, v121
	v_cvt_f32_i32_e32 v117, v117
	v_cvt_f32_i32_e32 v122, v122
	v_mul_f32_e32 v172, 0x3c010204, v238
	v_mul_f32_e32 v168, 0x3c010204, v243
	v_mul_f32_e32 v167, 0x3c010204, v239
	v_mul_f32_e32 v161, 0x3c010204, v240
	v_mul_f32_e32 v157, 0x3c010204, v241
	v_mul_f32_e32 v162, 0x3c010204, v244
	v_mul_f32_e32 v171, 0x3c010204, v242
	v_mul_f32_e32 v158, 0x3c010204, v245
	v_mul_f32_e32 v129, v168, v129
	v_mul_f32_e32 v125, v167, v125
	v_mul_f32_e32 v130, v162, v130
	v_mul_f32_e32 v128, v171, v128
	v_mul_f32_e32 v124, v172, v124
	v_max_f32_e32 v129, 0, v129
	v_max_f32_e32 v125, 0, v125
	v_max_f32_e32 v130, 0, v130
	v_mul_f32_e32 v126, v161, v126
	v_mul_f32_e32 v131, v158, v131
	v_max_f32_e32 v128, 0, v128
	v_max_f32_e32 v124, 0, v124
	v_max_f32_e32 v126, 0, v126
	v_max_f32_e32 v131, 0, v131
	v_mul_f32_e32 v127, v157, v127
	v_mul_f32_e32 v173, v124, v124
	v_max_f32_e32 v127, 0, v127
	v_mul_f32_e32 v178, v131, v131
	v_mul_f32_e32 v179, v127, v127
	v_mul_f32_e32 v169, 0x3c010204, v246
	v_add_u32_e32 v146, s63, v145
	v_mul_f32_e32 v164, 0x3c010204, v247
	v_ashrrev_i32_e32 v147, 31, v146
	v_mul_f32_e32 v159, 0x3c010204, v248
	v_mul_f32_e32 v155, 0x3c010204, v249
	v_lshlrev_b64 v[148:149], 7, v[146:147]
	v_lshl_add_u32 v145, v145, 2, v152
	v_lshl_add_u64 v[148:149], s[2:3], 0, v[148:149]
	s_waitcnt vmcnt(0)
	v_mul_f32_e32 v170, 0x3c010204, v174
	v_mul_f32_e32 v165, 0x3c010204, v175
	v_mul_f32_e32 v160, 0x3c010204, v176
	v_xor_b32_e32 v166, 64, v145
	v_xor_b32_e32 v163, 0x80, v145
	v_lshl_add_u64 v[150:151], v[148:149], 0, s[48:49]
	v_mov_b32_e32 v145, v114
	v_mul_f32_e32 v174, v129, v129
	v_mul_f32_e32 v176, v125, v125
	v_mul_f32_e32 v175, v130, v130
	v_mul_f32_e32 v156, 0x3c010204, v177
	v_lshl_add_u64 v[150:151], v[150:151], 0, v[144:145]
	v_mul_f32_e32 v145, v128, v128
	v_mul_f32_e32 v177, v126, v126
	v_cvt_pk_bf16_f32 v174, v145, v174
	v_cvt_pk_bf16_f32 v175, v175, v178
	v_cvt_pk_bf16_f32 v176, v173, v176
	v_mul_f32_e32 v118, v159, v118
	v_cvt_pk_bf16_f32 v177, v177, v179
	global_store_dwordx4 v[150:151], v[174:177], off
	v_mul_f32_e32 v120, v170, v120
	v_max_f32_e32 v145, 0, v120
	v_max_f32_e32 v176, 0, v118
	v_cvt_f32_i32_e32 v118, v123
	v_mul_f32_e32 v116, v169, v116
	v_mul_f32_e32 v121, v165, v121
	v_max_f32_e32 v173, 0, v116
	v_mul_f32_e32 v118, v156, v118
	v_max_f32_e32 v123, 0, v118
	v_cvt_f32_i32_e32 v118, v119
	v_mul_f32_e32 v116, v145, v145
	v_max_f32_e32 v174, 0, v121
	v_mul_f32_e32 v117, v164, v117
	v_mul_f32_e32 v122, v160, v122
	v_mul_f32_e32 v118, v155, v118
	s_mov_b32 s2, 0x10000
	v_max_f32_e32 v175, 0, v117
	v_mul_f32_e32 v117, v174, v174
	v_max_f32_e32 v122, 0, v122
	v_max_f32_e32 v179, 0, v118
	v_mul_f32_e32 v119, v123, v123
	v_cvt_pk_bf16_f32 v118, v116, v117
	v_add_co_u32_e32 v116, vcc, s2, v150
	v_mul_f32_e32 v120, v173, v173
	v_mul_f32_e32 v121, v175, v175
	v_mul_f32_e32 v177, v122, v122
	v_cvt_pk_bf16_f32 v119, v177, v119
	v_addc_co_u32_e32 v117, vcc, 0, v151, vcc
	v_mul_f32_e32 v178, v176, v176
	v_mul_f32_e32 v180, v179, v179
	v_cvt_pk_bf16_f32 v120, v120, v121
	v_cvt_pk_bf16_f32 v121, v178, v180
	global_store_dwordx4 v[116:117], v[118:121], off
	s_nop 1
	v_max_f32_e32 v118, v128, v124
	v_max_f32_e32 v119, v129, v125
	v_max3_f32 v118, v118, 0, v119
	v_max_f32_e32 v119, v130, v126
	v_max_f32_e32 v120, v131, v127
	v_max3_f32 v118, v118, v119, v120
	v_max_f32_e32 v119, v145, v173
	v_max_f32_e32 v120, v174, v175
	v_max3_f32 v118, v118, v119, v120
	v_max_f32_e32 v119, v122, v176
	v_max_f32_e32 v120, v123, v179
	v_max3_f32 v118, v118, v119, v120
	ds_bpermute_b32 v119, v166, v118
	s_waitcnt lgkmcnt(0)
	v_max_f32_e32 v119, v119, v119
	v_max_f32_e32 v118, v118, v119
	ds_bpermute_b32 v119, v163, v118
	s_and_saveexec_b64 s[8:9], s[42:43]
	s_cbranch_execz .LBB0_723
	s_lshl_b64 s[2:3], s[6:7], 2
	s_add_u32 s2, s61, s2
	s_waitcnt lgkmcnt(0)
	v_max_f32_e32 v119, v119, v119
	v_max_f32_e32 v118, v118, v118
	s_addc_u32 s3, s62, s3
	v_max_f32_e32 v120, v118, v119
	v_lshl_add_u64 v[118:119], v[146:147], 2, s[2:3]
	global_atomic_umax v[118:119], v120, off
